# norm phases: final-norm weight chunks loaded together; XN1/XN2 parameter vectors of chunks 1-3 issued with chunk 0 into free registers, counted waits
# baseline (speedup 1.0000x reference)
; template <int MODE> __device__ __forceinline__ void norm_row2(const float* xa, const float* xb, const float* nw, const float* sca, const float* sha, const float* scb, const float* shb, ...
;     const f32x4* pa = (const f32x4*)xa + lane; const f32x4* pb = (const f32x4*)xb + lane;
;     f32x4 va[4], vb[4]; float s0 = 0.f, s1 = 0.f;
; #pragma unroll
;     for (int j = 0; j < 4; ++j) { va[j] = pa[64 * j]; vb[j] = pb[64 * j]; }
; #pragma unroll
;     for (int j = 0; j < 4; ++j) { s0 += (va[j].x * va[j].x + va[j].y * va[j].y) + (va[j].z * va[j].z + va[j].w * va[j].w); s1 += (vb[j].x * vb[j].x + vb[j].y * vb[j].y) + (vb[j].z * vb[j].z + vb[j].w * vb[j].w); }
; #pragma unroll
;     for (int o = 1; o < 64; o <<= 1) { s0 += __shfl_xor(s0, o); s1 += __shfl_xor(s1, o); }
;     const float r0 = 1.f / sqrtf(s0 * (1.f / D) + eps), r1 = 1.f / sqrtf(s1 * (1.f / D) + eps);
; #pragma unroll
;     for (int j = 0; j < 4; ++j) { const f32x4 w = ((const f32x4*)nw)[64 * j + lane]; f32x4 ya = va[j] * r0 * w, yb = vb[j] * r1 * w;
;         if (MODE == 0) { const f32x4 ca = ((const f32x4*)sca)[64 * j + lane], ha = ((const f32x4*)sha)[64 * j + lane], cb = ((const f32x4*)scb)[64 * j + lane], hb = ((const f32x4*)shb)[64 * j + lane];
; __global__ void __launch_bounds__(512, 2) hymba_fwd(Args a) {
;     ...
;         for (int row = gw; row < TT; row += 2 * NGW) { const int rb_ = row + NGW; const int mb = batch_of_row(row); const float* xr = row < T_P ? a.in[0] + (size_t)row * D : a.in[1] + (size_t)(row - T_P) * D;
;             if (rb_ < TT) { const int mb2 = batch_of_row(rb_); const float* xr2 = rb_ < T_P ? a.in[0] + (size_t)rb_ * D : a.in[1] + (size_t)(rb_ - T_P) * D;
;                 norm_row2<0>(xr, xr2, a.in[6], MOD + mb * 6144 + 1024, MOD + mb * 6144, MOD + mb2 * 6144 + 1024, MOD + mb2 * 6144, XN + (size_t)row * D, XN + (size_t)rb_ * D, nullptr, nullptr, 1e-6f, lane); }
.LBB0_778:
	global_load_dwordx4 v[28:31], v44, s[24:25]
	global_load_dwordx4 v[24:27], v44, s[38:39]
	global_load_dwordx4 v[20:23], v44, s[24:25] offset:1024
	global_load_dwordx4 v[16:19], v44, s[38:39] offset:1024
	global_load_dwordx4 v[0:3], v44, s[24:25] offset:3072
	global_load_dwordx4 v[8:11], v44, s[24:25] offset:2048
	global_load_dwordx4 v[4:7], v44, s[38:39] offset:3072
	global_load_dwordx4 v[12:15], v44, s[38:39] offset:2048
	v_cmp_lt_i32_e32 vcc, v47, v46
	s_lshr_b32 s6, s6, 11
	s_ashr_i32 s3, s22, 14
	v_cndmask_b32_e32 v60, v45, v47, vcc
	v_cmp_lt_i32_e32 vcc, v48, v46
	v_lshlrev_b32_e32 v83, 2, v60
	s_add_i32 s6, s6, 2
	v_cndmask_b32_e32 v61, v45, v48, vcc
	v_cmp_lt_i32_e32 vcc, v49, v46
	v_lshlrev_b32_e32 v86, 2, v61
	s_and_b64 s[0:1], exec, s[0:1]
	v_cndmask_b32_e32 v62, v45, v49, vcc
	v_cmp_lt_i32_e32 vcc, v50, v46
	v_lshlrev_b32_e32 v87, 2, v62
	s_cselect_b32 s6, s3, s6
	v_cndmask_b32_e32 v63, v45, v50, vcc
	v_cmp_lt_i32_e32 vcc, v51, v46
	v_lshlrev_b32_e32 v88, 2, v63
	s_ashr_i32 s3, s2, 31
	v_cndmask_b32_e32 v64, v45, v51, vcc
	v_cmp_lt_i32_e32 vcc, v52, v46
	v_lshlrev_b32_e32 v89, 2, v64
	s_lshl_b64 s[0:1], s[2:3], 2
	v_cndmask_b32_e32 v65, v45, v52, vcc
	v_lshlrev_b32_e32 v90, 2, v65
	s_add_u32 s22, s34, s0
	s_addc_u32 s23, s35, s1
	s_mul_i32 s2, s6, 0x1800
	s_add_u32 s24, s22, 0x1000
	s_addc_u32 s25, s23, 0
	s_ashr_i32 s3, s2, 31
	s_lshl_b64 s[0:1], s[2:3], 2
	s_add_u32 s38, s34, s0
	s_addc_u32 s39, s35, s1
	global_load_dwordx4 v[56:59], v[32:33], off
	s_add_u32 s42, s38, 0x1000
	s_addc_u32 s43, s39, 0
	s_lshl_b64 s[26:27], s[26:27], 11
	s_waitcnt vmcnt(8)
	v_pk_mul_f32 v[60:61], v[30:31], v[30:31]
	v_pk_mul_f32 v[62:63], v[28:29], v[28:29]
	s_waitcnt vmcnt(7)
	v_pk_mul_f32 v[64:65], v[26:27], v[26:27]
	v_pk_mul_f32 v[66:67], v[24:25], v[24:25]
	s_waitcnt vmcnt(6)
	v_pk_mul_f32 v[68:69], v[22:23], v[22:23]
	v_pk_mul_f32 v[70:71], v[20:21], v[20:21]
	v_pk_mov_b32 v[84:85], v[62:63], v[60:61] op_sel:[1,0]
	v_mov_b32_e32 v63, v61
	v_pk_mov_b32 v[60:61], v[66:67], v[64:65] op_sel:[1,0]
	v_mov_b32_e32 v67, v65
	v_pk_mov_b32 v[64:65], v[70:71], v[68:69] op_sel:[1,0]
	v_mov_b32_e32 v71, v69
	s_waitcnt vmcnt(5)
	v_pk_mul_f32 v[72:73], v[18:19], v[18:19]
	v_pk_mul_f32 v[74:75], v[16:17], v[16:17]
	s_waitcnt vmcnt(3)
	v_mul_f32_e32 v76, v9, v9
	v_mul_f32_e32 v78, v11, v11
	v_pk_add_f32 v[62:63], v[84:85], v[62:63]
	v_pk_add_f32 v[64:65], v[64:65], v[70:71]
	v_mul_f32_e32 v91, v0, v0
	v_mul_f32_e32 v92, v1, v1
	v_mul_f32_e32 v93, v2, v2
	v_mul_f32_e32 v94, v3, v3
	v_pk_mov_b32 v[68:69], v[74:75], v[72:73] op_sel:[1,0]
	v_mov_b32_e32 v75, v73
	v_pk_fma_f32 v[72:73], v[8:9], v[8:9], v[76:77] op_sel_hi:[1,1,0]
	v_pk_fma_f32 v[76:77], v[10:11], v[10:11], v[78:79] op_sel_hi:[1,1,0]
	v_pk_add_f32 v[62:63], v[62:63], v[62:63] op_sel:[0,1] op_sel_hi:[1,0]
	v_pk_add_f32 v[64:65], v[64:65], v[64:65] op_sel:[0,1] op_sel_hi:[1,0]
	v_mov_b32_e32 v73, v93
	v_mov_b32_e32 v77, v94
	v_mov_b32_e32 v63, v91
	v_mov_b32_e32 v65, v92
	v_pk_add_f32 v[60:61], v[60:61], v[66:67]
	v_pk_add_f32 v[66:67], v[68:69], v[74:75]
	v_pk_add_f32 v[68:69], v[72:73], v[76:77]
	v_pk_add_f32 v[62:63], v[62:63], v[64:65]
	s_waitcnt vmcnt(1)
	v_mul_f32_e32 v80, v13, v13
	v_pk_add_f32 v[62:63], v[62:63], v[68:69]
	v_mul_f32_e32 v82, v15, v15
	v_add_f32_e32 v68, v62, v63
	ds_bpermute_b32 v69, v83, v68
	v_pk_add_f32 v[62:63], v[66:67], v[66:67] op_sel:[0,1] op_sel_hi:[1,0]
	v_mul_f32_e32 v95, v4, v4
	v_mul_f32_e32 v96, v5, v5
	v_mul_f32_e32 v97, v6, v6
	s_waitcnt lgkmcnt(0)
	v_add_f32_e32 v66, v68, v69
	ds_bpermute_b32 v67, v86, v66
	v_mul_f32_e32 v98, v7, v7
	v_pk_fma_f32 v[78:79], v[12:13], v[12:13], v[80:81] op_sel_hi:[1,1,0]
	v_pk_fma_f32 v[80:81], v[14:15], v[14:15], v[82:83] op_sel_hi:[1,1,0]
	v_pk_add_f32 v[60:61], v[60:61], v[60:61] op_sel:[0,1] op_sel_hi:[1,0]
	v_mov_b32_e32 v79, v97
	v_mov_b32_e32 v81, v98
	v_mov_b32_e32 v61, v95
	v_mov_b32_e32 v63, v96
	v_pk_add_f32 v[64:65], v[78:79], v[80:81]
	v_pk_add_f32 v[60:61], v[60:61], v[62:63]
	s_waitcnt lgkmcnt(0)
	v_add_f32_e32 v62, v66, v67
	v_pk_add_f32 v[60:61], v[60:61], v[64:65]
	ds_bpermute_b32 v63, v87, v62
	v_add_f32_e32 v60, v60, v61
	ds_bpermute_b32 v61, v83, v60
	s_waitcnt lgkmcnt(1)
	v_add_f32_e32 v70, v62, v63
	ds_bpermute_b32 v71, v88, v70
	s_waitcnt lgkmcnt(1)
	v_add_f32_e32 v68, v60, v61
	ds_bpermute_b32 v69, v86, v68
	global_load_dwordx4 v[60:63], v44, s[24:25]
	global_load_dwordx4 v[64:67], v44, s[22:23]
	s_waitcnt lgkmcnt(1)
	v_add_f32_e32 v70, v70, v71
	ds_bpermute_b32 v71, v89, v70
	s_waitcnt lgkmcnt(1)
	v_add_f32_e32 v68, v68, v69
	ds_bpermute_b32 v69, v87, v68
	s_waitcnt lgkmcnt(1)
	v_add_f32_e32 v70, v70, v71
	ds_bpermute_b32 v71, v90, v70
	s_waitcnt lgkmcnt(1)
	v_add_f32_e32 v68, v68, v69
	ds_bpermute_b32 v69, v88, v68
	s_waitcnt lgkmcnt(0)
	v_add_f32_e32 v76, v68, v69
	v_add_f32_e32 v68, v70, v71
	v_fmamk_f32 v78, v68, 0x3a800000, v42
	global_load_dwordx4 v[68:71], v44, s[42:43]
	global_load_dwordx4 v[72:75], v44, s[38:39]
	global_load_dwordx4 v[172:175], v[32:33], off offset:1024
	global_load_dwordx4 v[176:179], v53, s[24:25]
	global_load_dwordx4 v[180:183], v44, s[22:23] offset:1024
	global_load_dwordx4 v[184:187], v53, s[42:43]
	global_load_dwordx4 v[188:191], v44, s[38:39] offset:1024
	global_load_dwordx4 v[192:195], v[32:33], off offset:2048
	global_load_dwordx4 v[196:199], v54, s[24:25]
	global_load_dwordx4 v[200:203], v54, s[42:43]
	global_load_dwordx4 v[204:207], v44, s[22:23] offset:2048
	global_load_dwordx4 v[208:211], v44, s[38:39] offset:2048
	global_load_dwordx4 v[212:215], v[32:33], off offset:3072
	global_load_dwordx4 v[216:219], v55, s[24:25]
	global_load_dwordx4 v[220:223], v55, s[42:43]
	global_load_dwordx4 v[224:227], v44, s[22:23] offset:3072
	global_load_dwordx4 v[228:231], v44, s[38:39] offset:3072
	v_mul_f32_e32 v79, 0x4f800000, v78
	v_cmp_gt_f32_e32 vcc, s44, v78
	ds_bpermute_b32 v77, v89, v76
	s_waitcnt lgkmcnt(0)
; __device__ __forceinline__ unsigned pk2(float lo, float hi) { return f2bf(lo) | (f2bf(hi) << 16); }
; template <int MODE> __device__ __forceinline__ void norm_row2(const float* xa, const float* xb, const float* nw, const float* sca, const float* sha, const float* scb, const float* shb, ...
;     ...
;     const float r0 = 1.f / sqrtf(s0 * (1.f / D) + eps), r1 = 1.f / sqrtf(s1 * (1.f / D) + eps);
; #pragma unroll
;     for (int j = 0; j < 4; ++j) { const f32x4 w = ((const f32x4*)nw)[64 * j + lane]; f32x4 ya = va[j] * r0 * w, yb = vb[j] * r1 * w;
;         if (MODE == 0) { const f32x4 ca = ((const f32x4*)sca)[64 * j + lane], ha = ((const f32x4*)sha)[64 * j + lane], cb = ((const f32x4*)scb)[64 * j + lane], hb = ((const f32x4*)shb)[64 * j + lane];
;             ya = ya * (ca + 1.f) + ha; yb = yb * (cb + 1.f) + hb;
;             u32x2 o; o.x = pk2(ya.x, ya.y); o.y = pk2(ya.z, ya.w); ((u32x2*)oa)[64 * j + lane] = o; o.x = pk2(yb.x, yb.y); o.y = pk2(yb.z, yb.w); ((u32x2*)ob)[64 * j + lane] = o; }
	v_add_f32_e32 v76, v76, v77
	v_cndmask_b32_e32 v78, v78, v79, vcc
	v_sqrt_f32_e32 v79, v78
	ds_bpermute_b32 v77, v90, v76
	v_add_u32_e32 v80, -1, v79
	v_fma_f32 v81, -v80, v79, v78
	v_cmp_ge_f32_e64 s[0:1], 0, v81
	v_add_u32_e32 v81, 1, v79
	s_waitcnt lgkmcnt(0)
	v_add_f32_e32 v76, v76, v77
	v_cndmask_b32_e64 v80, v79, v80, s[0:1]
	v_fma_f32 v79, -v81, v79, v78
	v_cmp_lt_f32_e64 s[0:1], 0, v79
	v_fmamk_f32 v76, v76, 0x3a800000, v42
	v_mul_f32_e32 v82, 0x4f800000, v76
	v_cndmask_b32_e64 v79, v80, v81, s[0:1]
	v_mul_f32_e32 v80, 0x37800000, v79
	v_cndmask_b32_e32 v79, v79, v80, vcc
	v_cmp_class_f32_e32 vcc, v78, v43
	s_nop 1
	v_cndmask_b32_e32 v78, v79, v78, vcc
	v_div_scale_f32 v79, s[0:1], v78, v78, 1.0
	v_rcp_f32_e32 v80, v79
	v_cmp_gt_f32_e64 s[0:1], s44, v76
	v_fma_f32 v77, -v79, v80, 1.0
	s_nop 0
	v_cndmask_b32_e64 v76, v76, v82, s[0:1]
	v_fmac_f32_e32 v80, v77, v80
	v_div_scale_f32 v77, vcc, 1.0, v78, 1.0
	v_sqrt_f32_e32 v82, v76
	v_mul_f32_e32 v81, v77, v80
	v_fma_f32 v83, -v79, v81, v77
	v_fmac_f32_e32 v81, v83, v80
	v_fma_f32 v77, -v79, v81, v77
	v_add_u32_e32 v79, -1, v82
	v_fma_f32 v83, -v79, v82, v76
	v_cmp_ge_f32_e64 s[2:3], 0, v83
	v_add_u32_e32 v83, 1, v82
	s_nop 0
	v_cndmask_b32_e64 v79, v82, v79, s[2:3]
	v_fma_f32 v82, -v83, v82, v76
	v_cmp_lt_f32_e64 s[2:3], 0, v82
	s_nop 1
	v_cndmask_b32_e64 v79, v79, v83, s[2:3]
	v_mul_f32_e32 v82, 0x37800000, v79
	v_cndmask_b32_e64 v79, v79, v82, s[0:1]
	v_cmp_class_f32_e64 s[0:1], v76, v43
	s_nop 1
	v_cndmask_b32_e64 v79, v79, v76, s[0:1]
	v_div_scale_f32 v82, s[0:1], v79, v79, 1.0
	v_rcp_f32_e32 v83, v82
	v_div_fmas_f32 v76, v77, v80, v81
	v_div_fixup_f32 v76, v76, v78, 1.0
	v_fma_f32 v77, -v82, v83, 1.0
	v_fmac_f32_e32 v83, v77, v83
	v_div_scale_f32 v77, vcc, 1.0, v79, 1.0
	v_mul_f32_e32 v78, v77, v83
	v_fma_f32 v80, -v82, v78, v77
	v_fmac_f32_e32 v78, v80, v83
	v_fma_f32 v77, -v82, v78, v77
	v_div_fmas_f32 v77, v77, v83, v78
	v_div_fixup_f32 v78, v77, v79, 1.0
	v_pk_mul_f32 v[30:31], v[30:31], v[76:77] op_sel_hi:[1,0]
	v_pk_mul_f32 v[28:29], v[28:29], v[76:77] op_sel_hi:[1,0]
	v_pk_mul_f32 v[26:27], v[26:27], v[78:79] op_sel_hi:[1,0]
	v_pk_mul_f32 v[24:25], v[24:25], v[78:79] op_sel_hi:[1,0]
	s_waitcnt vmcnt(19)
	v_pk_mul_f32 v[28:29], v[56:57], v[28:29]
	v_pk_mul_f32 v[30:31], v[58:59], v[30:31]
	v_pk_mul_f32 v[24:25], v[56:57], v[24:25]
	v_pk_mul_f32 v[26:27], v[58:59], v[26:27]
	s_waitcnt vmcnt(18)
	v_pk_add_f32 v[56:57], v[62:63], 1.0 op_sel_hi:[1,0]
	v_pk_add_f32 v[58:59], v[60:61], 1.0 op_sel_hi:[1,0]
	s_waitcnt vmcnt(17)
	v_pk_fma_f32 v[30:31], v[56:57], v[30:31], v[66:67]
	v_pk_fma_f32 v[28:29], v[58:59], v[28:29], v[64:65]
	s_waitcnt vmcnt(16)
	v_pk_add_f32 v[56:57], v[70:71], 1.0 op_sel_hi:[1,0]
	v_pk_add_f32 v[58:59], v[68:69], 1.0 op_sel_hi:[1,0]
	s_waitcnt vmcnt(15)
	v_pk_fma_f32 v[26:27], v[56:57], v[26:27], v[74:75]
	v_bfe_u32 v56, v28, 16, 1
	v_add3_u32 v28, v28, v56, s45
	v_bfe_u32 v56, v29, 16, 1
	v_lshrrev_b32_e32 v28, 16, v28
	v_add3_u32 v29, v29, v56, s45
	v_and_or_b32 v28, v29, s56, v28
	v_bfe_u32 v29, v30, 16, 1
	v_add3_u32 v29, v30, v29, s45
	v_bfe_u32 v30, v31, 16, 1
	v_lshrrev_b32_e32 v29, 16, v29
	v_add3_u32 v30, v31, v30, s45
	v_add_co_u32_e32 v40, vcc, s57, v40
	v_pk_fma_f32 v[24:25], v[58:59], v[24:25], v[72:73]
	v_and_or_b32 v29, v30, s56, v29
	v_addc_co_u32_e32 v41, vcc, 0, v41, vcc
	global_store_dwordx2 v[40:41], v[28:29], off
	v_bfe_u32 v28, v24, 16, 1
	v_add3_u32 v24, v24, v28, s45
	v_bfe_u32 v28, v25, 16, 1
	v_lshrrev_b32_e32 v24, 16, v24
	v_add3_u32 v25, v25, v28, s45
	v_and_or_b32 v24, v25, s56, v24
	v_bfe_u32 v25, v26, 16, 1
	v_add3_u32 v25, v26, v25, s45
	v_bfe_u32 v26, v27, 16, 1
	v_lshrrev_b32_e32 v25, 16, v25
	v_add3_u32 v26, v27, v26, s45
	v_and_or_b32 v25, v26, s56, v25
	v_lshl_add_u64 v[68:69], v[34:35], 0, s[26:27]
	global_store_dwordx2 v[68:69], v[24:25], off
	s_nop 0
	v_pk_mul_f32 v[22:23], v[22:23], v[76:77] op_sel_hi:[1,0]
	v_pk_mul_f32 v[20:21], v[20:21], v[76:77] op_sel_hi:[1,0]
	v_pk_mul_f32 v[18:19], v[18:19], v[78:79] op_sel_hi:[1,0]
	v_pk_mul_f32 v[16:17], v[16:17], v[78:79] op_sel_hi:[1,0]
	v_pk_mul_f32 v[10:11], v[10:11], v[76:77] op_sel_hi:[1,0]
	v_pk_mul_f32 v[8:9], v[8:9], v[76:77] op_sel_hi:[1,0]
	v_pk_mul_f32 v[14:15], v[14:15], v[78:79] op_sel_hi:[1,0]
	v_pk_mul_f32 v[12:13], v[12:13], v[78:79] op_sel_hi:[1,0]
	v_pk_mul_f32 v[2:3], v[2:3], v[76:77] op_sel_hi:[1,0]
	v_pk_mul_f32 v[0:1], v[0:1], v[76:77] op_sel_hi:[1,0]
	v_pk_mul_f32 v[4:5], v[4:5], v[78:79] op_sel_hi:[1,0]
	v_pk_mul_f32 v[6:7], v[6:7], v[78:79] op_sel_hi:[1,0]
	s_waitcnt vmcnt(16)
; __device__ __forceinline__ unsigned pk2(float lo, float hi) { return f2bf(lo) | (f2bf(hi) << 16); }
; template <int MODE> __device__ __forceinline__ void norm_row2(const float* xa, const float* xb, const float* nw, const float* sca, const float* sha, const float* scb, const float* shb, ...
;     ...
;     for (int j = 0; j < 4; ++j) { const f32x4 w = ((const f32x4*)nw)[64 * j + lane]; f32x4 ya = va[j] * r0 * w, yb = vb[j] * r1 * w;
;         if (MODE == 0) { const f32x4 ca = ((const f32x4*)sca)[64 * j + lane], ha = ((const f32x4*)sha)[64 * j + lane], cb = ((const f32x4*)scb)[64 * j + lane], hb = ((const f32x4*)shb)[64 * j + lane];
;             ya = ya * (ca + 1.f) + ha; yb = yb * (cb + 1.f) + hb;
;             u32x2 o; o.x = pk2(ya.x, ya.y); o.y = pk2(ya.z, ya.w); ((u32x2*)oa)[64 * j + lane] = o; o.x = pk2(yb.x, yb.y); o.y = pk2(yb.z, yb.w); ((u32x2*)ob)[64 * j + lane] = o; }
	v_pk_mul_f32 v[20:21], v[20:21], v[172:173]
	v_pk_mul_f32 v[22:23], v[22:23], v[174:175]
	v_pk_mul_f32 v[16:17], v[172:173], v[16:17]
	v_pk_mul_f32 v[18:19], v[174:175], v[18:19]
	s_waitcnt vmcnt(15)
	v_pk_add_f32 v[24:25], v[178:179], 1.0 op_sel_hi:[1,0]
	v_pk_add_f32 v[26:27], v[176:177], 1.0 op_sel_hi:[1,0]
	s_waitcnt vmcnt(14)
	v_pk_fma_f32 v[22:23], v[22:23], v[24:25], v[182:183]
	v_pk_fma_f32 v[20:21], v[20:21], v[26:27], v[180:181]
	s_waitcnt vmcnt(13)
	v_pk_add_f32 v[24:25], v[186:187], 1.0 op_sel_hi:[1,0]
	v_pk_add_f32 v[26:27], v[184:185], 1.0 op_sel_hi:[1,0]
	s_waitcnt vmcnt(12)
	v_pk_fma_f32 v[18:19], v[18:19], v[24:25], v[190:191]
	v_bfe_u32 v24, v20, 16, 1
	v_add3_u32 v20, v20, v24, s45
	v_bfe_u32 v24, v21, 16, 1
	v_lshrrev_b32_e32 v20, 16, v20
	v_add3_u32 v21, v21, v24, s45
	v_and_or_b32 v20, v21, s56, v20
	v_bfe_u32 v21, v22, 16, 1
	v_add3_u32 v21, v22, v21, s45
	v_bfe_u32 v22, v23, 16, 1
	v_lshrrev_b32_e32 v21, 16, v21
	v_add3_u32 v22, v23, v22, s45
	v_pk_fma_f32 v[16:17], v[16:17], v[26:27], v[188:189]
	v_and_or_b32 v21, v22, s56, v21
	global_store_dwordx2 v[40:41], v[20:21], off offset:512
	v_bfe_u32 v20, v16, 16, 1
	v_add3_u32 v16, v16, v20, s45
	v_bfe_u32 v20, v17, 16, 1
	v_lshrrev_b32_e32 v16, 16, v16
	v_add3_u32 v17, v17, v20, s45
	v_and_or_b32 v16, v17, s56, v16
	v_bfe_u32 v17, v18, 16, 1
	v_add3_u32 v17, v18, v17, s45
	v_bfe_u32 v18, v19, 16, 1
	v_lshrrev_b32_e32 v17, 16, v17
	v_add3_u32 v18, v19, v18, s45
	v_and_or_b32 v17, v18, s56, v17
	global_store_dwordx2 v[68:69], v[16:17], off offset:512
	s_nop 0
	s_waitcnt vmcnt(13)
	v_pk_mul_f32 v[8:9], v[8:9], v[192:193]
	v_pk_mul_f32 v[10:11], v[10:11], v[194:195]
	v_pk_mul_f32 v[12:13], v[12:13], v[192:193]
	v_pk_mul_f32 v[14:15], v[14:15], v[194:195]
	s_waitcnt vmcnt(12)
	v_pk_add_f32 v[16:17], v[198:199], 1.0 op_sel_hi:[1,0]
	v_pk_add_f32 v[18:19], v[196:197], 1.0 op_sel_hi:[1,0]
	s_waitcnt vmcnt(11)
	v_pk_add_f32 v[20:21], v[202:203], 1.0 op_sel_hi:[1,0]
	v_pk_add_f32 v[22:23], v[200:201], 1.0 op_sel_hi:[1,0]
	s_waitcnt vmcnt(10)
	v_pk_fma_f32 v[10:11], v[10:11], v[16:17], v[206:207]
	v_pk_fma_f32 v[8:9], v[8:9], v[18:19], v[204:205]
	s_waitcnt vmcnt(9)
	v_pk_fma_f32 v[14:15], v[14:15], v[20:21], v[210:211]
	v_pk_fma_f32 v[12:13], v[12:13], v[22:23], v[208:209]
	v_bfe_u32 v16, v8, 16, 1
	v_bfe_u32 v18, v10, 16, 1
	v_bfe_u32 v17, v9, 16, 1
	v_bfe_u32 v19, v11, 16, 1
	v_bfe_u32 v20, v12, 16, 1
	v_bfe_u32 v22, v14, 16, 1
	v_add3_u32 v8, v8, v16, s45
	v_add3_u32 v10, v10, v18, s45
	v_bfe_u32 v21, v13, 16, 1
	v_bfe_u32 v23, v15, 16, 1
	v_add3_u32 v9, v9, v17, s45
	v_add3_u32 v11, v11, v19, s45
	v_add3_u32 v12, v12, v20, s45
	v_add3_u32 v14, v14, v22, s45
	v_lshrrev_b32_e32 v8, 16, v8
	v_lshrrev_b32_e32 v10, 16, v10
	v_add3_u32 v13, v13, v21, s45
	v_add3_u32 v15, v15, v23, s45
	v_lshrrev_b32_e32 v12, 16, v12
	v_lshrrev_b32_e32 v14, 16, v14
	v_and_or_b32 v8, v9, s56, v8
	v_and_or_b32 v9, v11, s56, v10
	v_and_or_b32 v10, v13, s56, v12
	v_and_or_b32 v11, v15, s56, v14
	global_store_dwordx2 v[40:41], v[8:9], off offset:1024
	global_store_dwordx2 v[68:69], v[10:11], off offset:1024
	s_nop 0
	s_waitcnt vmcnt(10)
	v_pk_mul_f32 v[0:1], v[0:1], v[212:213]
	v_pk_mul_f32 v[2:3], v[2:3], v[214:215]
	v_pk_mul_f32 v[6:7], v[6:7], v[214:215]
	v_pk_mul_f32 v[4:5], v[4:5], v[212:213]
	s_waitcnt vmcnt(9)
	v_pk_add_f32 v[8:9], v[218:219], 1.0 op_sel_hi:[1,0]
	v_pk_add_f32 v[10:11], v[216:217], 1.0 op_sel_hi:[1,0]
	s_waitcnt vmcnt(8)
	v_pk_add_f32 v[12:13], v[222:223], 1.0 op_sel_hi:[1,0]
	v_pk_add_f32 v[14:15], v[220:221], 1.0 op_sel_hi:[1,0]
	s_waitcnt vmcnt(7)
	v_pk_fma_f32 v[8:9], v[2:3], v[8:9], v[226:227]
	v_pk_fma_f32 v[10:11], v[0:1], v[10:11], v[224:225]
	s_waitcnt vmcnt(6)
	v_pk_fma_f32 v[0:1], v[4:5], v[14:15], v[228:229]
	v_pk_fma_f32 v[2:3], v[6:7], v[12:13], v[230:231]
	v_bfe_u32 v4, v10, 16, 1
	v_bfe_u32 v6, v8, 16, 1
	v_bfe_u32 v5, v11, 16, 1
	v_bfe_u32 v7, v9, 16, 1
	v_add3_u32 v4, v10, v4, s45
	v_add3_u32 v6, v8, v6, s45
	v_add3_u32 v5, v11, v5, s45
	v_add3_u32 v7, v9, v7, s45
	v_lshrrev_b32_e32 v4, 16, v4
	v_lshrrev_b32_e32 v6, 16, v6
	v_and_or_b32 v4, v5, s56, v4
	v_and_or_b32 v5, v7, s56, v6
	global_store_dwordx2 v[40:41], v[4:5], off offset:1536

; template <int MODE> __device__ __forceinline__ void norm_row2(const float* xa, const float* xb, const float* nw, const float* sca, const float* sha, const float* scb, const float* shb, ...
;     const f32x4* pa = (const f32x4*)xa + lane; const f32x4* pb = (const f32x4*)xb + lane;
;     f32x4 va[4], vb[4]; float s0 = 0.f, s1 = 0.f;
; #pragma unroll
;     for (int j = 0; j < 4; ++j) { va[j] = pa[64 * j]; vb[j] = pb[64 * j]; }
; #pragma unroll
;     for (int j = 0; j < 4; ++j) { s0 += (va[j].x * va[j].x + va[j].y * va[j].y) + (va[j].z * va[j].z + va[j].w * va[j].w); s1 += (vb[j].x * vb[j].x + vb[j].y * vb[j].y) + (vb[j].z * vb[j].z + vb[j].w * vb[j].w); }
; #pragma unroll
;     for (int o = 1; o < 64; o <<= 1) { s0 += __shfl_xor(s0, o); s1 += __shfl_xor(s1, o); }
;     const float r0 = 1.f / sqrtf(s0 * (1.f / D) + eps), r1 = 1.f / sqrtf(s1 * (1.f / D) + eps);
; __global__ void __launch_bounds__(512, 2) hymba_fwd(Args a) {
;     ...
;         for (int row = gw; row < TT; row += 2 * NGW) { const int rb_ = row + NGW; const int mb = batch_of_row(row);
;             if (rb_ < TT) { const int mb2 = batch_of_row(rb_);
;                 norm_row2<0>(a.out + (size_t)row * D, a.out + (size_t)rb_ * D, a.in[26], MOD + mb * 6144 + 4096, MOD + mb * 6144 + 3072, MOD + mb2 * 6144 + 4096, MOD + mb2 * 6144 + 3072, XN + (size_t)row * D, XN + (size_t)rb_ * D, nullptr, nullptr, 1e-6f, lane); }
.LBB0_1157:
	s_andn2_b64 vcc, exec, s[0:1]
	s_mov_b64 s[26:27], s[12:13]
	s_cbranch_vccnz .LBB0_1154
	global_load_dwordx4 v[24:27], v[12:13], off
	global_load_dwordx4 v[16:19], v[12:13], off offset:1024
	global_load_dwordx4 v[0:3], v[12:13], off offset:3072
	global_load_dwordx4 v[8:11], v[12:13], off offset:2048
	v_lshl_add_u64 v[12:13], s[22:23], 0, v[164:165]
	global_load_dwordx4 v[28:31], v[12:13], off
	global_load_dwordx4 v[20:23], v[12:13], off offset:1024
	global_load_dwordx4 v[4:7], v[12:13], off offset:3072
	s_nop 0
	global_load_dwordx4 v[12:15], v[12:13], off offset:2048
	v_cmp_lt_i32_e32 vcc, v42, v41
	s_add_i32 s1, s2, 0xffff8000
	s_lshr_b32 s1, s1, 11
	v_cndmask_b32_e32 v52, v40, v42, vcc
	v_cmp_lt_i32_e32 vcc, v43, v41
	v_lshlrev_b32_e32 v73, 2, v52
	s_ashr_i32 s0, s2, 14
	v_cndmask_b32_e32 v53, v40, v43, vcc
	v_cmp_lt_i32_e32 vcc, v44, v41
	v_lshlrev_b32_e32 v75, 2, v53
	s_add_i32 s1, s1, 2
	v_cndmask_b32_e32 v54, v40, v44, vcc
	v_cmp_lt_i32_e32 vcc, v45, v41
	v_lshlrev_b32_e32 v76, 2, v54
	s_cmp_lt_i32 s2, 0x8000
	v_cndmask_b32_e32 v55, v40, v45, vcc
	v_lshlrev_b32_e32 v77, 2, v55
	v_cmp_lt_i32_e32 vcc, v46, v41
	s_cselect_b32 s36, s0, s1
	s_ashr_i32 s3, s2, 31
	s_ashr_i32 s25, s24, 31
	s_lshl_b64 s[26:27], s[2:3], 10
	s_lshl_b64 s[0:1], s[24:25], 2
	s_add_u32 s0, s34, s0
	s_addc_u32 s1, s35, s1
	s_mul_i32 s2, s36, 0x1800
	s_add_u32 s36, s0, 0x4000
	s_addc_u32 s37, s1, 0
	s_add_u32 s24, s0, 0x3000
	s_addc_u32 s25, s1, 0
	s_ashr_i32 s3, s2, 31
	s_lshl_b64 s[0:1], s[2:3], 2
	s_add_u32 s0, s34, s0
	s_addc_u32 s1, s35, s1
	s_add_u32 s40, s0, 0x4000
	s_addc_u32 s41, s1, 0
	s_add_u32 s42, s0, 0x3000
	s_addc_u32 s43, s1, 0
	s_waitcnt vmcnt(0)
	v_pk_mul_f32 v[52:53], v[26:27], v[26:27]
	v_pk_mul_f32 v[54:55], v[24:25], v[24:25]
	v_pk_mul_f32 v[56:57], v[18:19], v[18:19]
	v_pk_mul_f32 v[58:59], v[16:17], v[16:17]
	v_pk_mov_b32 v[64:65], v[54:55], v[52:53] op_sel:[1,0]
	v_mov_b32_e32 v55, v53
	v_pk_mul_f32 v[52:53], v[30:31], v[30:31]
	v_pk_mul_f32 v[66:67], v[28:29], v[28:29]
	v_pk_mov_b32 v[68:69], v[58:59], v[56:57] op_sel:[1,0]
	v_mov_b32_e32 v59, v57
	v_mul_f32_e32 v60, v9, v9
	v_mul_f32_e32 v62, v11, v11
	v_pk_add_f32 v[54:55], v[64:65], v[54:55]
	v_pk_mov_b32 v[64:65], v[66:67], v[52:53] op_sel:[1,0]
	v_mov_b32_e32 v67, v53
	v_pk_add_f32 v[52:53], v[68:69], v[58:59]
	v_mul_f32_e32 v78, v0, v0
	v_mul_f32_e32 v79, v1, v1
	v_mul_f32_e32 v80, v2, v2
	v_mul_f32_e32 v81, v3, v3
	v_pk_fma_f32 v[60:61], v[8:9], v[8:9], v[60:61] op_sel_hi:[1,1,0]
	v_pk_fma_f32 v[62:63], v[10:11], v[10:11], v[62:63] op_sel_hi:[1,1,0]
	v_pk_add_f32 v[54:55], v[54:55], v[54:55] op_sel:[0,1] op_sel_hi:[1,0]
	v_pk_add_f32 v[52:53], v[52:53], v[52:53] op_sel:[0,1] op_sel_hi:[1,0]
	v_mov_b32_e32 v61, v80
	v_mov_b32_e32 v63, v81
	v_mov_b32_e32 v55, v78
	v_mov_b32_e32 v53, v79
	v_pk_add_f32 v[60:61], v[60:61], v[62:63]
	v_pk_add_f32 v[52:53], v[54:55], v[52:53]
	v_pk_mul_f32 v[56:57], v[22:23], v[22:23]
	v_pk_add_f32 v[52:53], v[52:53], v[60:61]
	v_pk_mul_f32 v[70:71], v[20:21], v[20:21]
	v_add_f32_e32 v60, v52, v53
	ds_bpermute_b32 v61, v73, v60
	v_mul_f32_e32 v72, v13, v13
	v_mul_f32_e32 v74, v15, v15
	v_mul_f32_e32 v84, v6, v6
	v_mul_f32_e32 v85, v7, v7
	v_pk_mov_b32 v[58:59], v[70:71], v[56:57] op_sel:[1,0]
	v_mov_b32_e32 v71, v57
	v_pk_fma_f32 v[56:57], v[12:13], v[12:13], v[72:73] op_sel_hi:[1,1,0]
	v_pk_fma_f32 v[68:69], v[14:15], v[14:15], v[74:75] op_sel_hi:[1,1,0]
	v_mov_b32_e32 v57, v84
	v_mov_b32_e32 v69, v85
	v_pk_add_f32 v[54:55], v[56:57], v[68:69]
	s_waitcnt lgkmcnt(0)
	v_add_f32_e32 v56, v60, v61
	v_pk_add_f32 v[64:65], v[64:65], v[66:67]
	v_pk_add_f32 v[58:59], v[58:59], v[70:71]
	ds_bpermute_b32 v57, v75, v56
	v_mul_f32_e32 v82, v4, v4
	v_mul_f32_e32 v83, v5, v5
	v_pk_add_f32 v[62:63], v[64:65], v[64:65] op_sel:[0,1] op_sel_hi:[1,0]
	v_pk_add_f32 v[52:53], v[58:59], v[58:59] op_sel:[0,1] op_sel_hi:[1,0]
	v_mov_b32_e32 v63, v82
	v_mov_b32_e32 v53, v83
	v_pk_add_f32 v[52:53], v[62:63], v[52:53]
	s_nop 0
	v_pk_add_f32 v[52:53], v[52:53], v[54:55]
	s_waitcnt lgkmcnt(0)
	v_add_f32_e32 v54, v56, v57
	v_add_f32_e32 v52, v52, v53
	ds_bpermute_b32 v53, v73, v52
	ds_bpermute_b32 v55, v76, v54
	s_waitcnt lgkmcnt(1)
	v_add_f32_e32 v52, v52, v53
	s_waitcnt lgkmcnt(0)
	v_add_f32_e32 v54, v54, v55
	ds_bpermute_b32 v53, v75, v52
	ds_bpermute_b32 v55, v77, v54
	s_waitcnt lgkmcnt(1)
	v_add_f32_e32 v52, v52, v53
	s_waitcnt lgkmcnt(0)
	v_add_f32_e32 v54, v54, v55
	v_cndmask_b32_e32 v55, v40, v46, vcc
	ds_bpermute_b32 v53, v76, v52
	v_lshlrev_b32_e32 v56, 2, v55
	ds_bpermute_b32 v55, v56, v54
	v_cmp_lt_i32_e32 vcc, v47, v41
	s_waitcnt lgkmcnt(1)
	v_add_f32_e32 v57, v52, v53
	v_cndmask_b32_e32 v52, v40, v47, vcc
	ds_bpermute_b32 v58, v77, v57
	s_waitcnt lgkmcnt(1)
	v_add_f32_e32 v59, v54, v55
	v_lshlrev_b32_e32 v72, 2, v52
	ds_bpermute_b32 v60, v72, v59
	global_load_dwordx4 v[52:55], v[32:33], off
	s_waitcnt lgkmcnt(1)
	v_add_f32_e32 v73, v57, v58
	ds_bpermute_b32 v74, v56, v73
	s_waitcnt lgkmcnt(1)
	v_add_f32_e32 v60, v59, v60
	global_load_dwordx4 v[56:59], v48, s[36:37]
	v_fmamk_f32 v75, v60, 0x3a800000, v38
	global_load_dwordx4 v[60:63], v48, s[24:25]
	global_load_dwordx4 v[64:67], v48, s[40:41]
	global_load_dwordx4 v[68:71], v48, s[42:43]
	global_load_dwordx4 v[172:175], v[32:33], off offset:1024
	global_load_dwordx4 v[176:179], v49, s[36:37]
	global_load_dwordx4 v[180:183], v49, s[24:25]
	global_load_dwordx4 v[184:187], v49, s[40:41]
	global_load_dwordx4 v[188:191], v49, s[42:43]
	global_load_dwordx4 v[192:195], v[32:33], off offset:2048
	global_load_dwordx4 v[196:199], v50, s[36:37]
	global_load_dwordx4 v[200:203], v50, s[40:41]
	global_load_dwordx4 v[204:207], v50, s[24:25]
	global_load_dwordx4 v[208:211], v50, s[42:43]
	global_load_dwordx4 v[212:215], v[32:33], off offset:3072
	global_load_dwordx4 v[216:219], v51, s[36:37]
	global_load_dwordx4 v[220:223], v51, s[40:41]
	global_load_dwordx4 v[224:227], v51, s[24:25]
	global_load_dwordx4 v[228:231], v51, s[42:43]
	v_mul_f32_e32 v76, 0x4f800000, v75
	v_cmp_gt_f32_e32 vcc, s7, v75
	s_waitcnt lgkmcnt(0)
; __device__ __forceinline__ unsigned pk2(float lo, float hi) { return f2bf(lo) | (f2bf(hi) << 16); }
; template <int MODE> __device__ __forceinline__ void norm_row2(const float* xa, const float* xb, const float* nw, const float* sca, const float* sha, const float* scb, const float* shb, ...
;     ...
;     const float r0 = 1.f / sqrtf(s0 * (1.f / D) + eps), r1 = 1.f / sqrtf(s1 * (1.f / D) + eps);
; #pragma unroll
;     for (int j = 0; j < 4; ++j) { const f32x4 w = ((const f32x4*)nw)[64 * j + lane]; f32x4 ya = va[j] * r0 * w, yb = vb[j] * r1 * w;
;         if (MODE == 0) { const f32x4 ca = ((const f32x4*)sca)[64 * j + lane], ha = ((const f32x4*)sha)[64 * j + lane], cb = ((const f32x4*)scb)[64 * j + lane], hb = ((const f32x4*)shb)[64 * j + lane];
;             ya = ya * (ca + 1.f) + ha; yb = yb * (cb + 1.f) + hb;
;             u32x2 o; o.x = pk2(ya.x, ya.y); o.y = pk2(ya.z, ya.w); ((u32x2*)oa)[64 * j + lane] = o; o.x = pk2(yb.x, yb.y); o.y = pk2(yb.z, yb.w); ((u32x2*)ob)[64 * j + lane] = o; }
	v_add_f32_e32 v73, v73, v74
	ds_bpermute_b32 v72, v72, v73
	v_cndmask_b32_e32 v75, v75, v76, vcc
	v_sqrt_f32_e32 v76, v75
	s_waitcnt lgkmcnt(0)
	v_add_f32_e32 v72, v73, v72
	v_add_u32_e32 v74, -1, v76
	v_fma_f32 v77, -v74, v76, v75
	v_cmp_ge_f32_e64 s[0:1], 0, v77
	v_add_u32_e32 v77, 1, v76
	v_fmamk_f32 v72, v72, 0x3a800000, v38
	v_cndmask_b32_e64 v74, v76, v74, s[0:1]
	v_fma_f32 v76, -v77, v76, v75
	v_cmp_lt_f32_e64 s[0:1], 0, v76
	v_mul_f32_e32 v78, 0x4f800000, v72
	s_nop 0
	v_cndmask_b32_e64 v74, v74, v77, s[0:1]
	v_mul_f32_e32 v76, 0x37800000, v74
	v_cndmask_b32_e32 v74, v74, v76, vcc
	v_cmp_class_f32_e32 vcc, v75, v39
	s_nop 1
	v_cndmask_b32_e32 v74, v74, v75, vcc
	v_div_scale_f32 v75, s[0:1], v74, v74, 1.0
	v_rcp_f32_e32 v76, v75
	v_cmp_gt_f32_e64 s[0:1], s7, v72
	v_fma_f32 v73, -v75, v76, 1.0
	s_nop 0
	v_cndmask_b32_e64 v72, v72, v78, s[0:1]
	v_fmac_f32_e32 v76, v73, v76
	v_div_scale_f32 v73, vcc, 1.0, v74, 1.0
	v_sqrt_f32_e32 v78, v72
	v_mul_f32_e32 v77, v73, v76
	v_fma_f32 v79, -v75, v77, v73
	v_fmac_f32_e32 v77, v79, v76
	v_fma_f32 v73, -v75, v77, v73
	v_add_u32_e32 v75, -1, v78
	v_fma_f32 v79, -v75, v78, v72
	v_cmp_ge_f32_e64 s[2:3], 0, v79
	v_add_u32_e32 v79, 1, v78
	s_nop 0
	v_cndmask_b32_e64 v75, v78, v75, s[2:3]
	v_fma_f32 v78, -v79, v78, v72
	v_cmp_lt_f32_e64 s[2:3], 0, v78
	s_nop 1
	v_cndmask_b32_e64 v75, v75, v79, s[2:3]
	v_mul_f32_e32 v78, 0x37800000, v75
	v_cndmask_b32_e64 v75, v75, v78, s[0:1]
	v_cmp_class_f32_e64 s[0:1], v72, v39
	s_nop 1
	v_cndmask_b32_e64 v75, v75, v72, s[0:1]
	v_div_scale_f32 v78, s[0:1], v75, v75, 1.0
	v_rcp_f32_e32 v79, v78
	v_div_fmas_f32 v72, v73, v76, v77
	v_div_fixup_f32 v72, v72, v74, 1.0
	v_fma_f32 v73, -v78, v79, 1.0
	v_fmac_f32_e32 v79, v73, v79
	v_div_scale_f32 v73, vcc, 1.0, v75, 1.0
	v_mul_f32_e32 v74, v73, v79
	v_fma_f32 v76, -v78, v74, v73
	v_fmac_f32_e32 v74, v76, v79
	v_fma_f32 v73, -v78, v74, v73
	v_div_fmas_f32 v73, v73, v79, v74
	v_div_fixup_f32 v74, v73, v75, 1.0
	v_pk_mul_f32 v[26:27], v[26:27], v[72:73] op_sel_hi:[1,0]
	v_pk_mul_f32 v[24:25], v[24:25], v[72:73] op_sel_hi:[1,0]
	v_pk_mul_f32 v[30:31], v[30:31], v[74:75] op_sel_hi:[1,0]
	v_pk_mul_f32 v[28:29], v[28:29], v[74:75] op_sel_hi:[1,0]
	s_waitcnt vmcnt(19)
	v_pk_mul_f32 v[24:25], v[52:53], v[24:25]
	v_pk_mul_f32 v[26:27], v[54:55], v[26:27]
	v_pk_mul_f32 v[28:29], v[52:53], v[28:29]
	v_pk_mul_f32 v[30:31], v[54:55], v[30:31]
	s_waitcnt vmcnt(18)
	v_pk_add_f32 v[52:53], v[58:59], 1.0 op_sel_hi:[1,0]
	v_pk_add_f32 v[54:55], v[56:57], 1.0 op_sel_hi:[1,0]
	s_waitcnt vmcnt(17)
	v_pk_fma_f32 v[26:27], v[52:53], v[26:27], v[62:63]
	v_pk_fma_f32 v[24:25], v[54:55], v[24:25], v[60:61]
	s_waitcnt vmcnt(16)
	v_pk_add_f32 v[52:53], v[66:67], 1.0 op_sel_hi:[1,0]
	v_pk_add_f32 v[54:55], v[64:65], 1.0 op_sel_hi:[1,0]
	s_waitcnt vmcnt(15)
	v_pk_fma_f32 v[30:31], v[52:53], v[30:31], v[70:71]
	v_bfe_u32 v52, v24, 16, 1
	v_add3_u32 v24, v24, v52, s44
	v_bfe_u32 v52, v25, 16, 1
	v_lshrrev_b32_e32 v24, 16, v24
	v_add3_u32 v25, v25, v52, s44
	v_and_or_b32 v24, v25, s45, v24
	v_bfe_u32 v25, v26, 16, 1
	v_add3_u32 v25, v26, v25, s44
	v_bfe_u32 v26, v27, 16, 1
	v_lshrrev_b32_e32 v25, 16, v25
	v_add3_u32 v26, v27, v26, s44
	v_add_co_u32_e32 v36, vcc, s52, v36
	v_pk_fma_f32 v[28:29], v[54:55], v[28:29], v[68:69]
	v_and_or_b32 v25, v26, s45, v25
	v_addc_co_u32_e32 v37, vcc, 0, v37, vcc
	global_store_dwordx2 v[36:37], v[24:25], off
	v_bfe_u32 v24, v28, 16, 1
	v_add3_u32 v24, v28, v24, s44
	v_bfe_u32 v25, v29, 16, 1
	v_lshrrev_b32_e32 v24, 16, v24
	v_add3_u32 v25, v29, v25, s44
	v_and_or_b32 v24, v25, s45, v24
	v_bfe_u32 v25, v30, 16, 1
	v_add3_u32 v25, v30, v25, s44
	v_bfe_u32 v26, v31, 16, 1
	v_lshrrev_b32_e32 v25, 16, v25
	v_add3_u32 v26, v31, v26, s44
	v_and_or_b32 v25, v26, s45, v25
	v_lshl_add_u64 v[26:27], s[20:21], 0, v[166:167]
	v_add_co_u32_e32 v64, vcc, s52, v26
	v_pk_mul_f32 v[18:19], v[18:19], v[72:73] op_sel_hi:[1,0]
	s_nop 0
	v_addc_co_u32_e32 v65, vcc, 0, v27, vcc
	global_store_dwordx2 v[64:65], v[24:25], off
	s_nop 0
	v_pk_mul_f32 v[16:17], v[16:17], v[72:73] op_sel_hi:[1,0]
	v_pk_mul_f32 v[22:23], v[22:23], v[74:75] op_sel_hi:[1,0]
	v_pk_mul_f32 v[20:21], v[20:21], v[74:75] op_sel_hi:[1,0]
	v_pk_mul_f32 v[10:11], v[10:11], v[72:73] op_sel_hi:[1,0]
	v_pk_mul_f32 v[8:9], v[8:9], v[72:73] op_sel_hi:[1,0]
	v_pk_mul_f32 v[14:15], v[14:15], v[74:75] op_sel_hi:[1,0]
	v_pk_mul_f32 v[12:13], v[12:13], v[74:75] op_sel_hi:[1,0]
	v_pk_mul_f32 v[2:3], v[2:3], v[72:73] op_sel_hi:[1,0]
	v_pk_mul_f32 v[0:1], v[0:1], v[72:73] op_sel_hi:[1,0]
	v_pk_mul_f32 v[4:5], v[4:5], v[74:75] op_sel_hi:[1,0]
	v_pk_mul_f32 v[6:7], v[6:7], v[74:75] op_sel_hi:[1,0]
	s_waitcnt vmcnt(16)
; __device__ __forceinline__ unsigned pk2(float lo, float hi) { return f2bf(lo) | (f2bf(hi) << 16); }
; template <int MODE> __device__ __forceinline__ void norm_row2(const float* xa, const float* xb, const float* nw, const float* sca, const float* sha, const float* scb, const float* shb, ...
;     ...
;     for (int j = 0; j < 4; ++j) { const f32x4 w = ((const f32x4*)nw)[64 * j + lane]; f32x4 ya = va[j] * r0 * w, yb = vb[j] * r1 * w;
;         if (MODE == 0) { const f32x4 ca = ((const f32x4*)sca)[64 * j + lane], ha = ((const f32x4*)sha)[64 * j + lane], cb = ((const f32x4*)scb)[64 * j + lane], hb = ((const f32x4*)shb)[64 * j + lane];
;             ya = ya * (ca + 1.f) + ha; yb = yb * (cb + 1.f) + hb;
;             u32x2 o; o.x = pk2(ya.x, ya.y); o.y = pk2(ya.z, ya.w); ((u32x2*)oa)[64 * j + lane] = o; o.x = pk2(yb.x, yb.y); o.y = pk2(yb.z, yb.w); ((u32x2*)ob)[64 * j + lane] = o; }
	v_pk_mul_f32 v[16:17], v[16:17], v[172:173]
	v_pk_mul_f32 v[18:19], v[18:19], v[174:175]
	v_pk_mul_f32 v[20:21], v[172:173], v[20:21]
	v_pk_mul_f32 v[22:23], v[174:175], v[22:23]
	s_waitcnt vmcnt(15)
	v_pk_add_f32 v[24:25], v[178:179], 1.0 op_sel_hi:[1,0]
	v_pk_add_f32 v[26:27], v[176:177], 1.0 op_sel_hi:[1,0]
	s_waitcnt vmcnt(14)
	v_pk_fma_f32 v[18:19], v[18:19], v[24:25], v[182:183]
	v_pk_fma_f32 v[16:17], v[16:17], v[26:27], v[180:181]
	s_waitcnt vmcnt(13)
	v_pk_add_f32 v[24:25], v[186:187], 1.0 op_sel_hi:[1,0]
	v_pk_add_f32 v[26:27], v[184:185], 1.0 op_sel_hi:[1,0]
	s_waitcnt vmcnt(12)
	v_pk_fma_f32 v[22:23], v[22:23], v[24:25], v[190:191]
	v_bfe_u32 v24, v16, 16, 1
	v_add3_u32 v16, v16, v24, s44
	v_bfe_u32 v24, v17, 16, 1
	v_lshrrev_b32_e32 v16, 16, v16
	v_add3_u32 v17, v17, v24, s44
	v_and_or_b32 v16, v17, s45, v16
	v_bfe_u32 v17, v18, 16, 1
	v_add3_u32 v17, v18, v17, s44
	v_bfe_u32 v18, v19, 16, 1
	v_lshrrev_b32_e32 v17, 16, v17
	v_add3_u32 v18, v19, v18, s44
	v_pk_fma_f32 v[20:21], v[20:21], v[26:27], v[188:189]
	v_and_or_b32 v17, v18, s45, v17
	global_store_dwordx2 v[36:37], v[16:17], off offset:512
	v_bfe_u32 v16, v20, 16, 1
	v_add3_u32 v16, v20, v16, s44
	v_bfe_u32 v17, v21, 16, 1
	v_lshrrev_b32_e32 v16, 16, v16
	v_add3_u32 v17, v21, v17, s44
	v_and_or_b32 v16, v17, s45, v16
	v_bfe_u32 v17, v22, 16, 1
	v_add3_u32 v17, v22, v17, s44
	v_bfe_u32 v18, v23, 16, 1
	v_lshrrev_b32_e32 v17, 16, v17
	v_add3_u32 v18, v23, v18, s44
	v_and_or_b32 v17, v18, s45, v17
	global_store_dwordx2 v[64:65], v[16:17], off offset:512
	s_nop 0
	s_waitcnt vmcnt(13)
	v_pk_mul_f32 v[8:9], v[8:9], v[192:193]
	v_pk_mul_f32 v[10:11], v[10:11], v[194:195]
	v_pk_mul_f32 v[12:13], v[12:13], v[192:193]
	v_pk_mul_f32 v[14:15], v[14:15], v[194:195]
	s_waitcnt vmcnt(12)
	v_pk_add_f32 v[16:17], v[198:199], 1.0 op_sel_hi:[1,0]
	v_pk_add_f32 v[18:19], v[196:197], 1.0 op_sel_hi:[1,0]
	s_waitcnt vmcnt(10)
	v_pk_fma_f32 v[10:11], v[10:11], v[16:17], v[206:207]
	v_pk_fma_f32 v[8:9], v[8:9], v[18:19], v[204:205]
	v_bfe_u32 v18, v10, 16, 1
	v_bfe_u32 v16, v8, 16, 1
	v_bfe_u32 v17, v9, 16, 1
	v_bfe_u32 v19, v11, 16, 1
	v_add3_u32 v8, v8, v16, s44
	v_add3_u32 v10, v10, v18, s44
	v_pk_add_f32 v[20:21], v[202:203], 1.0 op_sel_hi:[1,0]
	v_pk_add_f32 v[22:23], v[200:201], 1.0 op_sel_hi:[1,0]
	v_add3_u32 v9, v9, v17, s44
	v_add3_u32 v11, v11, v19, s44
	v_lshrrev_b32_e32 v8, 16, v8
	v_lshrrev_b32_e32 v10, 16, v10
	s_waitcnt vmcnt(9)
	v_pk_fma_f32 v[14:15], v[14:15], v[20:21], v[210:211]
	v_pk_fma_f32 v[12:13], v[12:13], v[22:23], v[208:209]
	v_and_or_b32 v8, v9, s45, v8
	v_and_or_b32 v9, v11, s45, v10
	v_bfe_u32 v20, v12, 16, 1
	global_store_dwordx2 v[36:37], v[8:9], off offset:1024
	v_bfe_u32 v9, v14, 16, 1
	v_add3_u32 v12, v12, v20, s44
	v_bfe_u32 v8, v13, 16, 1
	v_add3_u32 v9, v14, v9, s44
	v_bfe_u32 v10, v15, 16, 1
	v_lshrrev_b32_e32 v12, 16, v12
	v_add3_u32 v8, v13, v8, s44
	v_lshrrev_b32_e32 v9, 16, v9
	v_add3_u32 v10, v15, v10, s44
	v_and_or_b32 v8, v8, s45, v12
	v_and_or_b32 v9, v10, s45, v9
	global_store_dwordx2 v[64:65], v[8:9], off offset:1024
	s_nop 0
	s_waitcnt vmcnt(10)
	v_pk_mul_f32 v[0:1], v[0:1], v[212:213]
	v_pk_mul_f32 v[2:3], v[2:3], v[214:215]
	v_pk_mul_f32 v[6:7], v[6:7], v[214:215]
	v_pk_mul_f32 v[4:5], v[4:5], v[212:213]
	s_waitcnt vmcnt(9)
	v_pk_add_f32 v[8:9], v[218:219], 1.0 op_sel_hi:[1,0]
	v_pk_add_f32 v[10:11], v[216:217], 1.0 op_sel_hi:[1,0]
	s_waitcnt vmcnt(8)
	v_pk_add_f32 v[12:13], v[222:223], 1.0 op_sel_hi:[1,0]
	v_pk_add_f32 v[14:15], v[220:221], 1.0 op_sel_hi:[1,0]
	s_waitcnt vmcnt(7)
	v_pk_fma_f32 v[8:9], v[2:3], v[8:9], v[226:227]
	v_pk_fma_f32 v[10:11], v[0:1], v[10:11], v[224:225]
	s_waitcnt vmcnt(6)
	v_pk_fma_f32 v[0:1], v[4:5], v[14:15], v[228:229]
	v_pk_fma_f32 v[2:3], v[6:7], v[12:13], v[230:231]
	v_bfe_u32 v4, v10, 16, 1
	v_bfe_u32 v6, v8, 16, 1
	v_bfe_u32 v5, v11, 16, 1
	v_bfe_u32 v7, v9, 16, 1
	v_add3_u32 v4, v10, v4, s44
	v_add3_u32 v6, v8, v6, s44
	v_add3_u32 v5, v11, v5, s44
	v_add3_u32 v7, v9, v7, s44
	v_lshrrev_b32_e32 v4, 16, v4
	v_lshrrev_b32_e32 v6, 16, v6
	v_and_or_b32 v4, v5, s45, v4
	v_and_or_b32 v5, v7, s45, v6
	global_store_dwordx2 v[36:37], v[4:5], off offset:1536
	s_branch .LBB0_1154
